# v105 + nt hint on stores whose consumer is far away: gla-in Q and G outputs (read only in G3) and the G1 decay tiles (read only in G3)
# baseline (speedup 1.0000x reference)
.LBB0_517:
	s_cmp_gt_u32 s36, 7
	s_cselect_b32 s98, 1, 0
	s_cmp_lt_u32 s36, 2
	s_cselect_b32 s98, 1, s98
	v_pk_mul_f32 v[138:139], v[124:125], s[56:57] op_sel_hi:[1,0]
	v_pk_mul_f32 v[124:125], v[122:123], s[56:57] op_sel_hi:[1,0]
	v_cndmask_b32_e64 v122, 0, 1, s[60:61]
	v_pk_mul_f32 v[126:127], v[126:127], s[56:57] op_sel_hi:[1,0]
	v_cmp_ne_u32_e64 s[40:41], 1, v122
	s_andn2_b64 vcc, exec, s[60:61]
	v_pk_mul_f32 v[140:141], v[120:121], s[56:57] op_sel_hi:[1,0]
	s_cbranch_vccnz .LBB0_519
	v_mul_f32_e32 v121, 0xbfb8aa3b, v140
	v_exp_f32_e32 v121, v121
	v_mul_f32_e32 v120, 0xbfb8aa3b, v138
	v_exp_f32_e32 v120, v120
	v_mul_f32_e32 v161, 0xbfb8aa3b, v124
	v_add_f32_e32 v121, 1.0, v121
	v_rcp_f32_e32 v122, v121
	v_mul_f32_e32 v121, 0xbfb8aa3b, v139
	v_exp_f32_e32 v121, v121
	v_add_f32_e32 v120, 1.0, v120
	v_exp_f32_e32 v161, v161
	v_rcp_f32_e32 v120, v120
	v_add_f32_e32 v121, 1.0, v121
	v_rcp_f32_e32 v121, v121
	v_add_f32_e32 v161, 1.0, v161
	v_mul_f32_e32 v123, 0xbfb8aa3b, v141
	v_mul_f32_e32 v160, 0xbfb8aa3b, v126
	v_rcp_f32_e32 v162, v161
	v_mul_f32_e32 v161, 0xbfb8aa3b, v127
	v_pk_mul_f32 v[138:139], v[138:139], v[120:121]
	v_mul_f32_e32 v120, 0xbfb8aa3b, v125
	v_exp_f32_e32 v123, v123
	v_exp_f32_e32 v160, v160
	v_exp_f32_e32 v161, v161
	v_exp_f32_e32 v120, v120
	v_add_f32_e32 v123, 1.0, v123
	v_add_f32_e32 v160, 1.0, v160
	v_add_f32_e32 v161, 1.0, v161
	v_add_f32_e32 v120, 1.0, v120
	v_rcp_f32_e32 v123, v123
	v_rcp_f32_e32 v160, v160
	v_rcp_f32_e32 v161, v161
	v_rcp_f32_e32 v163, v120
	v_pk_mul_f32 v[140:141], v[140:141], v[122:123]
	v_pk_mul_f32 v[126:127], v[126:127], v[160:161]
	v_pk_mul_f32 v[124:125], v[124:125], v[162:163]
.LBB0_519:
	v_lshl_add_u32 v160, s2, 8, v156
	v_add_u32_e32 v120, s37, v158
	v_ashrrev_i32_e32 v122, 31, v160
	v_ashrrev_i32_e32 v121, 31, v120
	v_mul_lo_u32 v161, s54, v122
	v_mul_lo_u32 v162, s55, v160
	v_mad_u64_u32 v[122:123], s[28:29], s54, v160, 0
	s_mov_b32 s57, s56
	v_lshl_add_u64 v[120:121], v[120:121], 1, s[58:59]
	v_add3_u32 v123, v123, v161, v162
	s_mov_b32 s58, s56
	s_mov_b32 s59, s56
	v_lshl_add_u64 v[122:123], v[122:123], 1, v[120:121]
	v_pk_mul_f32 v[118:119], v[118:119], s[58:59]
	v_pk_mul_f32 v[116:117], v[116:117], s[56:57]
	v_pk_mul_f32 v[114:115], v[114:115], s[58:59]
	s_and_b64 vcc, exec, s[40:41]
	v_pk_mul_f32 v[112:113], v[112:113], s[56:57]
	v_cvt_pk_bf16_f32 v138, v138, v139
	v_cvt_pk_bf16_f32 v139, v126, v127
	v_cvt_pk_bf16_f32 v140, v140, v141
	v_cvt_pk_bf16_f32 v141, v124, v125
	s_nop 0
	s_bitcmp1_b32 s98, 0
	s_cbranch_scc0 .Lgi_keep0
	global_store_dwordx4 v[122:123], v[138:141], off sc1 nt
	s_branch .Lgi_done0
.Lgi_keep0:
	global_store_dwordx4 v[122:123], v[138:141], off sc1
.Lgi_done0:
	s_nop 1
	s_cbranch_vccnz .LBB0_521
	v_mul_f32_e32 v125, 0xbfb8aa3b, v112
	v_exp_f32_e32 v125, v125
	v_mul_f32_e32 v124, 0xbfb8aa3b, v116
	v_exp_f32_e32 v124, v124
	v_mul_f32_e32 v139, 0xbfb8aa3b, v114
	v_add_f32_e32 v125, 1.0, v125
	v_rcp_f32_e32 v126, v125
	v_mul_f32_e32 v125, 0xbfb8aa3b, v117
	v_exp_f32_e32 v125, v125
	v_add_f32_e32 v124, 1.0, v124
	v_exp_f32_e32 v139, v139
	v_rcp_f32_e32 v124, v124
	v_add_f32_e32 v125, 1.0, v125
	v_rcp_f32_e32 v125, v125
	v_add_f32_e32 v139, 1.0, v139
	v_mul_f32_e32 v127, 0xbfb8aa3b, v113
	v_mul_f32_e32 v138, 0xbfb8aa3b, v118
	v_rcp_f32_e32 v140, v139
	v_mul_f32_e32 v139, 0xbfb8aa3b, v119
	v_pk_mul_f32 v[116:117], v[116:117], v[124:125]
	v_mul_f32_e32 v124, 0xbfb8aa3b, v115
	v_exp_f32_e32 v127, v127
	v_exp_f32_e32 v138, v138
	v_exp_f32_e32 v139, v139
	v_exp_f32_e32 v124, v124
	v_add_f32_e32 v127, 1.0, v127
	v_add_f32_e32 v138, 1.0, v138
	v_add_f32_e32 v139, 1.0, v139
	v_add_f32_e32 v124, 1.0, v124
	v_rcp_f32_e32 v127, v127
	v_rcp_f32_e32 v138, v138
	v_rcp_f32_e32 v139, v139
	v_rcp_f32_e32 v141, v124
	v_pk_mul_f32 v[112:113], v[112:113], v[126:127]
	v_pk_mul_f32 v[118:119], v[118:119], v[138:139]
	v_pk_mul_f32 v[114:115], v[114:115], v[140:141]
.LBB0_521:
	s_mov_b64 s[4:5], 0x100
	v_cvt_pk_bf16_f32 v116, v116, v117
	v_cvt_pk_bf16_f32 v117, v118, v119
	v_cvt_pk_bf16_f32 v118, v112, v113
	v_pk_mul_f32 v[110:111], v[110:111], s[58:59]
	v_pk_mul_f32 v[108:109], v[108:109], s[56:57]
	v_pk_mul_f32 v[106:107], v[106:107], s[58:59]
	s_and_b64 vcc, exec, s[40:41]
	v_pk_mul_f32 v[112:113], v[104:105], s[56:57]
	v_lshl_add_u64 v[122:123], v[122:123], 0, s[4:5]
	v_cvt_pk_bf16_f32 v119, v114, v115
	s_nop 0
	s_bitcmp1_b32 s98, 0
	s_cbranch_scc0 .Lgi_keep1
	global_store_dwordx4 v[122:123], v[116:119], off sc1 nt
	s_branch .Lgi_done1
.Lgi_keep1:
	global_store_dwordx4 v[122:123], v[116:119], off sc1
.Lgi_done1:
	s_nop 1
	s_cbranch_vccnz .LBB0_523
	v_mul_f32_e32 v105, 0xbfb8aa3b, v112
	v_exp_f32_e32 v105, v105
	v_mul_f32_e32 v104, 0xbfb8aa3b, v108
	v_exp_f32_e32 v104, v104
	v_mul_f32_e32 v117, 0xbfb8aa3b, v106
	v_add_f32_e32 v105, 1.0, v105
	v_rcp_f32_e32 v114, v105
	v_mul_f32_e32 v105, 0xbfb8aa3b, v109
	v_exp_f32_e32 v105, v105
	v_add_f32_e32 v104, 1.0, v104
	v_exp_f32_e32 v117, v117
	v_rcp_f32_e32 v104, v104
	v_add_f32_e32 v105, 1.0, v105
	v_rcp_f32_e32 v105, v105
	v_add_f32_e32 v117, 1.0, v117
	v_mul_f32_e32 v115, 0xbfb8aa3b, v113
	v_mul_f32_e32 v116, 0xbfb8aa3b, v110
	v_rcp_f32_e32 v118, v117
	v_mul_f32_e32 v117, 0xbfb8aa3b, v111
	v_pk_mul_f32 v[108:109], v[108:109], v[104:105]
	v_mul_f32_e32 v104, 0xbfb8aa3b, v107
	v_exp_f32_e32 v115, v115
	v_exp_f32_e32 v116, v116
	v_exp_f32_e32 v117, v117
	v_exp_f32_e32 v104, v104
	v_add_f32_e32 v115, 1.0, v115
	v_add_f32_e32 v116, 1.0, v116
	v_add_f32_e32 v117, 1.0, v117
	v_add_f32_e32 v104, 1.0, v104
	v_rcp_f32_e32 v115, v115
	v_rcp_f32_e32 v116, v116
	v_rcp_f32_e32 v117, v117
	v_rcp_f32_e32 v119, v104
	v_pk_mul_f32 v[112:113], v[112:113], v[114:115]
	v_pk_mul_f32 v[110:111], v[110:111], v[116:117]
	v_pk_mul_f32 v[106:107], v[106:107], v[118:119]
.LBB0_523:
	v_or_b32_e32 v104, 16, v160
	v_mul_lo_u32 v114, s55, v104
	v_mad_u64_u32 v[104:105], s[28:29], s54, v104, 0
	v_add3_u32 v105, v105, v161, v114
	s_mov_b32 s58, s56
	s_mov_b32 s59, s56
	v_lshl_add_u64 v[104:105], v[104:105], 1, v[120:121]
	v_pk_mul_f32 v[102:103], v[102:103], s[58:59]
	v_pk_mul_f32 v[100:101], v[100:101], s[56:57]
	v_pk_mul_f32 v[98:99], v[98:99], s[58:59]
	s_and_b64 vcc, exec, s[40:41]
	v_pk_mul_f32 v[96:97], v[96:97], s[56:57]
	v_cvt_pk_bf16_f32 v108, v108, v109
	v_cvt_pk_bf16_f32 v109, v110, v111
	v_cvt_pk_bf16_f32 v110, v112, v113
	v_cvt_pk_bf16_f32 v111, v106, v107
	s_nop 0
	s_bitcmp1_b32 s98, 0
	s_cbranch_scc0 .Lgi_keep2
	global_store_dwordx4 v[104:105], v[108:111], off sc1 nt
	s_branch .Lgi_done2
.Lgi_keep2:
	global_store_dwordx4 v[104:105], v[108:111], off sc1
.Lgi_done2:
	s_nop 1
	s_cbranch_vccnz .LBB0_525
	v_mul_f32_e32 v107, 0xbfb8aa3b, v96
	v_exp_f32_e32 v107, v107
	v_mul_f32_e32 v106, 0xbfb8aa3b, v100
	v_exp_f32_e32 v106, v106
	v_mul_f32_e32 v111, 0xbfb8aa3b, v98
	v_add_f32_e32 v107, 1.0, v107
	v_rcp_f32_e32 v108, v107
	v_mul_f32_e32 v107, 0xbfb8aa3b, v101
	v_exp_f32_e32 v107, v107
	v_add_f32_e32 v106, 1.0, v106
	v_exp_f32_e32 v111, v111
	v_rcp_f32_e32 v106, v106
	v_add_f32_e32 v107, 1.0, v107
	v_rcp_f32_e32 v107, v107
	v_add_f32_e32 v111, 1.0, v111
	v_mul_f32_e32 v109, 0xbfb8aa3b, v97
	v_mul_f32_e32 v110, 0xbfb8aa3b, v102
	v_rcp_f32_e32 v112, v111
	v_mul_f32_e32 v111, 0xbfb8aa3b, v103
	v_pk_mul_f32 v[100:101], v[100:101], v[106:107]
	v_mul_f32_e32 v106, 0xbfb8aa3b, v99
	v_exp_f32_e32 v109, v109
	v_exp_f32_e32 v110, v110
	v_exp_f32_e32 v111, v111
	v_exp_f32_e32 v106, v106
	v_add_f32_e32 v109, 1.0, v109
	v_add_f32_e32 v110, 1.0, v110
	v_add_f32_e32 v111, 1.0, v111
	v_add_f32_e32 v106, 1.0, v106
	v_rcp_f32_e32 v109, v109
	v_rcp_f32_e32 v110, v110
	v_rcp_f32_e32 v111, v111
	v_rcp_f32_e32 v113, v106
	v_pk_mul_f32 v[96:97], v[96:97], v[108:109]
	v_pk_mul_f32 v[102:103], v[102:103], v[110:111]
	v_pk_mul_f32 v[98:99], v[98:99], v[112:113]
.LBB0_525:
	v_cvt_pk_bf16_f32 v100, v100, v101
	v_cvt_pk_bf16_f32 v101, v102, v103
	v_cvt_pk_bf16_f32 v102, v96, v97
	v_pk_mul_f32 v[94:95], v[94:95], s[58:59]
	v_pk_mul_f32 v[92:93], v[92:93], s[56:57]
	v_pk_mul_f32 v[90:91], v[90:91], s[58:59]
	s_and_b64 vcc, exec, s[40:41]
	v_pk_mul_f32 v[96:97], v[88:89], s[56:57]
	v_lshl_add_u64 v[104:105], v[104:105], 0, s[4:5]
	v_cvt_pk_bf16_f32 v103, v98, v99
	s_nop 0
	s_bitcmp1_b32 s98, 0
	s_cbranch_scc0 .Lgi_keep3
	global_store_dwordx4 v[104:105], v[100:103], off sc1 nt
	s_branch .Lgi_done3
.Lgi_keep3:
	global_store_dwordx4 v[104:105], v[100:103], off sc1
.Lgi_done3:
	s_nop 1
	s_cbranch_vccnz .LBB0_527
	v_mul_f32_e32 v89, 0xbfb8aa3b, v96
	v_exp_f32_e32 v89, v89
	v_mul_f32_e32 v88, 0xbfb8aa3b, v92
	v_exp_f32_e32 v88, v88
	v_mul_f32_e32 v101, 0xbfb8aa3b, v90
	v_add_f32_e32 v89, 1.0, v89
	v_rcp_f32_e32 v98, v89
	v_mul_f32_e32 v89, 0xbfb8aa3b, v93
	v_exp_f32_e32 v89, v89
	v_add_f32_e32 v88, 1.0, v88
	v_exp_f32_e32 v101, v101
	v_rcp_f32_e32 v88, v88
	v_add_f32_e32 v89, 1.0, v89
	v_rcp_f32_e32 v89, v89
	v_add_f32_e32 v101, 1.0, v101
	v_mul_f32_e32 v99, 0xbfb8aa3b, v97
	v_mul_f32_e32 v100, 0xbfb8aa3b, v94
	v_rcp_f32_e32 v102, v101
	v_mul_f32_e32 v101, 0xbfb8aa3b, v95
	v_pk_mul_f32 v[92:93], v[92:93], v[88:89]
	v_mul_f32_e32 v88, 0xbfb8aa3b, v91
	v_exp_f32_e32 v99, v99
	v_exp_f32_e32 v100, v100
	v_exp_f32_e32 v101, v101
	v_exp_f32_e32 v88, v88
	v_add_f32_e32 v99, 1.0, v99
	v_add_f32_e32 v100, 1.0, v100
	v_add_f32_e32 v101, 1.0, v101
	v_add_f32_e32 v88, 1.0, v88
	v_rcp_f32_e32 v99, v99
	v_rcp_f32_e32 v100, v100
	v_rcp_f32_e32 v101, v101
	v_rcp_f32_e32 v103, v88
	v_pk_mul_f32 v[96:97], v[96:97], v[98:99]
	v_pk_mul_f32 v[94:95], v[94:95], v[100:101]
	v_pk_mul_f32 v[90:91], v[90:91], v[102:103]
.LBB0_527:
	v_or_b32_e32 v88, 32, v160
	v_mul_lo_u32 v98, s55, v88
	v_mad_u64_u32 v[88:89], s[28:29], s54, v88, 0
	v_add3_u32 v89, v89, v161, v98
	s_mov_b32 s58, s56
	s_mov_b32 s59, s56
	v_lshl_add_u64 v[88:89], v[88:89], 1, v[120:121]
	v_pk_mul_f32 v[86:87], v[86:87], s[58:59]
	v_pk_mul_f32 v[84:85], v[84:85], s[56:57]
	v_pk_mul_f32 v[82:83], v[82:83], s[58:59]
	s_and_b64 vcc, exec, s[40:41]
	v_pk_mul_f32 v[80:81], v[80:81], s[56:57]
	v_cvt_pk_bf16_f32 v92, v92, v93
	v_cvt_pk_bf16_f32 v93, v94, v95
	v_cvt_pk_bf16_f32 v94, v96, v97
	v_cvt_pk_bf16_f32 v95, v90, v91
	s_nop 0
	s_bitcmp1_b32 s98, 0
	s_cbranch_scc0 .Lgi_keep4
	global_store_dwordx4 v[88:89], v[92:95], off sc1 nt
	s_branch .Lgi_done4
.Lgi_keep4:
	global_store_dwordx4 v[88:89], v[92:95], off sc1
.Lgi_done4:
	s_nop 1
	s_cbranch_vccnz .LBB0_529
	v_mul_f32_e32 v91, 0xbfb8aa3b, v80
	v_exp_f32_e32 v91, v91
	v_mul_f32_e32 v90, 0xbfb8aa3b, v84
	v_exp_f32_e32 v90, v90
	v_mul_f32_e32 v95, 0xbfb8aa3b, v82
	v_add_f32_e32 v91, 1.0, v91
	v_rcp_f32_e32 v92, v91
	v_mul_f32_e32 v91, 0xbfb8aa3b, v85
	v_exp_f32_e32 v91, v91
	v_add_f32_e32 v90, 1.0, v90
	v_exp_f32_e32 v95, v95
	v_rcp_f32_e32 v90, v90
	v_add_f32_e32 v91, 1.0, v91
	v_rcp_f32_e32 v91, v91
	v_add_f32_e32 v95, 1.0, v95
	v_mul_f32_e32 v93, 0xbfb8aa3b, v81
	v_mul_f32_e32 v94, 0xbfb8aa3b, v86
	v_rcp_f32_e32 v96, v95
	v_mul_f32_e32 v95, 0xbfb8aa3b, v87
	v_pk_mul_f32 v[84:85], v[84:85], v[90:91]
	v_mul_f32_e32 v90, 0xbfb8aa3b, v83
	v_exp_f32_e32 v93, v93
	v_exp_f32_e32 v94, v94
	v_exp_f32_e32 v95, v95
	v_exp_f32_e32 v90, v90
	v_add_f32_e32 v93, 1.0, v93
	v_add_f32_e32 v94, 1.0, v94
	v_add_f32_e32 v95, 1.0, v95
	v_add_f32_e32 v90, 1.0, v90
	v_rcp_f32_e32 v93, v93
	v_rcp_f32_e32 v94, v94
	v_rcp_f32_e32 v95, v95
	v_rcp_f32_e32 v97, v90
	v_pk_mul_f32 v[80:81], v[80:81], v[92:93]
	v_pk_mul_f32 v[86:87], v[86:87], v[94:95]
	v_pk_mul_f32 v[82:83], v[82:83], v[96:97]
.LBB0_529:
	v_cvt_pk_bf16_f32 v84, v84, v85
	v_cvt_pk_bf16_f32 v85, v86, v87
	v_cvt_pk_bf16_f32 v86, v80, v81
	v_pk_mul_f32 v[78:79], v[78:79], s[58:59]
	v_pk_mul_f32 v[76:77], v[76:77], s[56:57]
	v_pk_mul_f32 v[74:75], v[74:75], s[58:59]
	s_and_b64 vcc, exec, s[40:41]
	v_pk_mul_f32 v[80:81], v[72:73], s[56:57]
	v_lshl_add_u64 v[88:89], v[88:89], 0, s[4:5]
	v_cvt_pk_bf16_f32 v87, v82, v83
	s_nop 0
	s_bitcmp1_b32 s98, 0
	s_cbranch_scc0 .Lgi_keep5
	global_store_dwordx4 v[88:89], v[84:87], off sc1 nt
	s_branch .Lgi_done5
.Lgi_keep5:
	global_store_dwordx4 v[88:89], v[84:87], off sc1
.Lgi_done5:
	s_nop 1
	s_cbranch_vccnz .LBB0_531
	v_mul_f32_e32 v73, 0xbfb8aa3b, v80
	v_exp_f32_e32 v73, v73
	v_mul_f32_e32 v72, 0xbfb8aa3b, v76
	v_exp_f32_e32 v72, v72
	v_mul_f32_e32 v85, 0xbfb8aa3b, v74
	v_add_f32_e32 v73, 1.0, v73
	v_rcp_f32_e32 v82, v73
	v_mul_f32_e32 v73, 0xbfb8aa3b, v77
	v_exp_f32_e32 v73, v73
	v_add_f32_e32 v72, 1.0, v72
	v_exp_f32_e32 v85, v85
	v_rcp_f32_e32 v72, v72
	v_add_f32_e32 v73, 1.0, v73
	v_rcp_f32_e32 v73, v73
	v_add_f32_e32 v85, 1.0, v85
	v_mul_f32_e32 v83, 0xbfb8aa3b, v81
	v_mul_f32_e32 v84, 0xbfb8aa3b, v78
	v_rcp_f32_e32 v86, v85
	v_mul_f32_e32 v85, 0xbfb8aa3b, v79
	v_pk_mul_f32 v[76:77], v[76:77], v[72:73]
	v_mul_f32_e32 v72, 0xbfb8aa3b, v75
	v_exp_f32_e32 v83, v83
	v_exp_f32_e32 v84, v84
	v_exp_f32_e32 v85, v85
	v_exp_f32_e32 v72, v72
	v_add_f32_e32 v83, 1.0, v83
	v_add_f32_e32 v84, 1.0, v84
	v_add_f32_e32 v85, 1.0, v85
	v_add_f32_e32 v72, 1.0, v72
	v_rcp_f32_e32 v83, v83
	v_rcp_f32_e32 v84, v84
	v_rcp_f32_e32 v85, v85
	v_rcp_f32_e32 v87, v72
	v_pk_mul_f32 v[80:81], v[80:81], v[82:83]
	v_pk_mul_f32 v[78:79], v[78:79], v[84:85]
	v_pk_mul_f32 v[74:75], v[74:75], v[86:87]
.LBB0_531:
	v_or_b32_e32 v72, 48, v160
	v_mul_lo_u32 v82, s55, v72
	v_mad_u64_u32 v[72:73], s[28:29], s54, v72, 0
	v_add3_u32 v73, v73, v161, v82
	s_mov_b32 s58, s56
	s_mov_b32 s59, s56
	v_lshl_add_u64 v[72:73], v[72:73], 1, v[120:121]
	v_pk_mul_f32 v[70:71], v[70:71], s[58:59]
	v_pk_mul_f32 v[68:69], v[68:69], s[56:57]
	v_pk_mul_f32 v[66:67], v[66:67], s[58:59]
	s_and_b64 vcc, exec, s[40:41]
	v_pk_mul_f32 v[64:65], v[64:65], s[56:57]
	v_cvt_pk_bf16_f32 v76, v76, v77
	v_cvt_pk_bf16_f32 v77, v78, v79
	v_cvt_pk_bf16_f32 v78, v80, v81
	v_cvt_pk_bf16_f32 v79, v74, v75
	s_nop 0
	s_bitcmp1_b32 s98, 0
	s_cbranch_scc0 .Lgi_keep6
	global_store_dwordx4 v[72:73], v[76:79], off sc1 nt
	s_branch .Lgi_done6
.Lgi_keep6:
	global_store_dwordx4 v[72:73], v[76:79], off sc1
.Lgi_done6:
	s_nop 1
	s_cbranch_vccnz .LBB0_533
	v_mul_f32_e32 v75, 0xbfb8aa3b, v64
	v_exp_f32_e32 v75, v75
	v_mul_f32_e32 v74, 0xbfb8aa3b, v68
	v_exp_f32_e32 v74, v74
	v_mul_f32_e32 v79, 0xbfb8aa3b, v66
	v_add_f32_e32 v75, 1.0, v75
	v_rcp_f32_e32 v76, v75
	v_mul_f32_e32 v75, 0xbfb8aa3b, v69
	v_exp_f32_e32 v75, v75
	v_add_f32_e32 v74, 1.0, v74
	v_exp_f32_e32 v79, v79
	v_rcp_f32_e32 v74, v74
	v_add_f32_e32 v75, 1.0, v75
	v_rcp_f32_e32 v75, v75
	v_add_f32_e32 v79, 1.0, v79
	v_mul_f32_e32 v77, 0xbfb8aa3b, v65
	v_mul_f32_e32 v78, 0xbfb8aa3b, v70
	v_rcp_f32_e32 v80, v79
	v_mul_f32_e32 v79, 0xbfb8aa3b, v71
	v_pk_mul_f32 v[68:69], v[68:69], v[74:75]
	v_mul_f32_e32 v74, 0xbfb8aa3b, v67
	v_exp_f32_e32 v77, v77
	v_exp_f32_e32 v78, v78
	v_exp_f32_e32 v79, v79
	v_exp_f32_e32 v74, v74
	v_add_f32_e32 v77, 1.0, v77
	v_add_f32_e32 v78, 1.0, v78
	v_add_f32_e32 v79, 1.0, v79
	v_add_f32_e32 v74, 1.0, v74
	v_rcp_f32_e32 v77, v77
	v_rcp_f32_e32 v78, v78
	v_rcp_f32_e32 v79, v79
	v_rcp_f32_e32 v81, v74
	v_pk_mul_f32 v[64:65], v[64:65], v[76:77]
	v_pk_mul_f32 v[70:71], v[70:71], v[78:79]
	v_pk_mul_f32 v[66:67], v[66:67], v[80:81]
.LBB0_533:
	v_cvt_pk_bf16_f32 v68, v68, v69
	v_cvt_pk_bf16_f32 v69, v70, v71
	v_cvt_pk_bf16_f32 v70, v64, v65
	v_pk_mul_f32 v[62:63], v[62:63], s[58:59]
	v_pk_mul_f32 v[60:61], v[60:61], s[56:57]
	v_pk_mul_f32 v[58:59], v[58:59], s[58:59]
	s_and_b64 vcc, exec, s[40:41]
	v_pk_mul_f32 v[64:65], v[56:57], s[56:57]
	v_lshl_add_u64 v[72:73], v[72:73], 0, s[4:5]
	v_cvt_pk_bf16_f32 v71, v66, v67
	s_nop 0
	s_bitcmp1_b32 s98, 0
	s_cbranch_scc0 .Lgi_keep7
	global_store_dwordx4 v[72:73], v[68:71], off sc1 nt
	s_branch .Lgi_done7
.Lgi_keep7:
	global_store_dwordx4 v[72:73], v[68:71], off sc1
.Lgi_done7:
	s_nop 1
	s_cbranch_vccnz .LBB0_535
	v_mul_f32_e32 v57, 0xbfb8aa3b, v64
	v_exp_f32_e32 v57, v57
	v_mul_f32_e32 v56, 0xbfb8aa3b, v60
	v_exp_f32_e32 v56, v56
	v_mul_f32_e32 v69, 0xbfb8aa3b, v58
	v_add_f32_e32 v57, 1.0, v57
	v_rcp_f32_e32 v66, v57
	v_mul_f32_e32 v57, 0xbfb8aa3b, v61
	v_exp_f32_e32 v57, v57
	v_add_f32_e32 v56, 1.0, v56
	v_exp_f32_e32 v69, v69
	v_rcp_f32_e32 v56, v56
	v_add_f32_e32 v57, 1.0, v57
	v_rcp_f32_e32 v57, v57
	v_add_f32_e32 v69, 1.0, v69
	v_mul_f32_e32 v67, 0xbfb8aa3b, v65
	v_mul_f32_e32 v68, 0xbfb8aa3b, v62
	v_rcp_f32_e32 v70, v69
	v_mul_f32_e32 v69, 0xbfb8aa3b, v63
	v_pk_mul_f32 v[60:61], v[60:61], v[56:57]
	v_mul_f32_e32 v56, 0xbfb8aa3b, v59
	v_exp_f32_e32 v67, v67
	v_exp_f32_e32 v68, v68
	v_exp_f32_e32 v69, v69
	v_exp_f32_e32 v56, v56
	v_add_f32_e32 v67, 1.0, v67
	v_add_f32_e32 v68, 1.0, v68
	v_add_f32_e32 v69, 1.0, v69
	v_add_f32_e32 v56, 1.0, v56
	v_rcp_f32_e32 v67, v67
	v_rcp_f32_e32 v68, v68
	v_rcp_f32_e32 v69, v69
	v_rcp_f32_e32 v71, v56
	v_pk_mul_f32 v[64:65], v[64:65], v[66:67]
	v_pk_mul_f32 v[62:63], v[62:63], v[68:69]
	v_pk_mul_f32 v[58:59], v[58:59], v[70:71]
.LBB0_535:
	v_add_u32_e32 v56, 0x80, v160
	v_ashrrev_i32_e32 v57, 31, v56
	v_mul_lo_u32 v66, s54, v57
	v_mul_lo_u32 v67, s55, v56
	v_mad_u64_u32 v[56:57], s[28:29], s54, v56, 0
	v_add3_u32 v57, v57, v66, v67
	s_mov_b32 s58, s56
	s_mov_b32 s59, s56
	v_lshl_add_u64 v[56:57], v[56:57], 1, v[120:121]
	v_pk_mul_f32 v[54:55], v[54:55], s[58:59]
	v_pk_mul_f32 v[52:53], v[52:53], s[56:57]
	v_pk_mul_f32 v[50:51], v[50:51], s[58:59]
	s_and_b64 vcc, exec, s[40:41]
	v_pk_mul_f32 v[48:49], v[48:49], s[56:57]
	v_cvt_pk_bf16_f32 v60, v60, v61
	v_cvt_pk_bf16_f32 v61, v62, v63
	v_cvt_pk_bf16_f32 v62, v64, v65
	v_cvt_pk_bf16_f32 v63, v58, v59
	s_nop 0
	s_bitcmp1_b32 s98, 0
	s_cbranch_scc0 .Lgi_keep8
	global_store_dwordx4 v[56:57], v[60:63], off sc1 nt
	s_branch .Lgi_done8
.Lgi_keep8:
	global_store_dwordx4 v[56:57], v[60:63], off sc1
.Lgi_done8:
	s_nop 1
	s_cbranch_vccnz .LBB0_537
	v_mul_f32_e32 v59, 0xbfb8aa3b, v48
	v_exp_f32_e32 v59, v59
	v_mul_f32_e32 v58, 0xbfb8aa3b, v52
	v_exp_f32_e32 v58, v58
	v_mul_f32_e32 v63, 0xbfb8aa3b, v50
	v_add_f32_e32 v59, 1.0, v59
	v_rcp_f32_e32 v60, v59
	v_mul_f32_e32 v59, 0xbfb8aa3b, v53
	v_exp_f32_e32 v59, v59
	v_add_f32_e32 v58, 1.0, v58
	v_exp_f32_e32 v63, v63
	v_rcp_f32_e32 v58, v58
	v_add_f32_e32 v59, 1.0, v59
	v_rcp_f32_e32 v59, v59
	v_add_f32_e32 v63, 1.0, v63
	v_mul_f32_e32 v61, 0xbfb8aa3b, v49
	v_mul_f32_e32 v62, 0xbfb8aa3b, v54
	v_rcp_f32_e32 v64, v63
	v_mul_f32_e32 v63, 0xbfb8aa3b, v55
	v_pk_mul_f32 v[52:53], v[52:53], v[58:59]
	v_mul_f32_e32 v58, 0xbfb8aa3b, v51
	v_exp_f32_e32 v61, v61
	v_exp_f32_e32 v62, v62
	v_exp_f32_e32 v63, v63
	v_exp_f32_e32 v58, v58
	v_add_f32_e32 v61, 1.0, v61
	v_add_f32_e32 v62, 1.0, v62
	v_add_f32_e32 v63, 1.0, v63
	v_add_f32_e32 v58, 1.0, v58
	v_rcp_f32_e32 v61, v61
	v_rcp_f32_e32 v62, v62
	v_rcp_f32_e32 v63, v63
	v_rcp_f32_e32 v65, v58
	v_pk_mul_f32 v[48:49], v[48:49], v[60:61]
	v_pk_mul_f32 v[54:55], v[54:55], v[62:63]
	v_pk_mul_f32 v[50:51], v[50:51], v[64:65]
.LBB0_537:
	v_cvt_pk_bf16_f32 v52, v52, v53
	v_cvt_pk_bf16_f32 v53, v54, v55
	v_cvt_pk_bf16_f32 v54, v48, v49
	v_pk_mul_f32 v[46:47], v[46:47], s[58:59]
	v_pk_mul_f32 v[44:45], v[44:45], s[56:57]
	v_pk_mul_f32 v[42:43], v[42:43], s[58:59]
	s_and_b64 vcc, exec, s[40:41]
	v_pk_mul_f32 v[48:49], v[40:41], s[56:57]
	v_lshl_add_u64 v[56:57], v[56:57], 0, s[4:5]
	v_cvt_pk_bf16_f32 v55, v50, v51
	s_nop 0
	s_bitcmp1_b32 s98, 0
	s_cbranch_scc0 .Lgi_keep9
	global_store_dwordx4 v[56:57], v[52:55], off sc1 nt
	s_branch .Lgi_done9
.Lgi_keep9:
	global_store_dwordx4 v[56:57], v[52:55], off sc1
.Lgi_done9:
	s_nop 1
	s_cbranch_vccnz .LBB0_539
	v_mul_f32_e32 v41, 0xbfb8aa3b, v48
	v_exp_f32_e32 v41, v41
	v_mul_f32_e32 v40, 0xbfb8aa3b, v44
	v_exp_f32_e32 v40, v40
	v_mul_f32_e32 v53, 0xbfb8aa3b, v42
	v_add_f32_e32 v41, 1.0, v41
	v_rcp_f32_e32 v50, v41
	v_mul_f32_e32 v41, 0xbfb8aa3b, v45
	v_exp_f32_e32 v41, v41
	v_add_f32_e32 v40, 1.0, v40
	v_exp_f32_e32 v53, v53
	v_rcp_f32_e32 v40, v40
	v_add_f32_e32 v41, 1.0, v41
	v_rcp_f32_e32 v41, v41
	v_add_f32_e32 v53, 1.0, v53
	v_mul_f32_e32 v51, 0xbfb8aa3b, v49
	v_mul_f32_e32 v52, 0xbfb8aa3b, v46
	v_rcp_f32_e32 v54, v53
	v_mul_f32_e32 v53, 0xbfb8aa3b, v47
	v_pk_mul_f32 v[44:45], v[44:45], v[40:41]
	v_mul_f32_e32 v40, 0xbfb8aa3b, v43
	v_exp_f32_e32 v51, v51
	v_exp_f32_e32 v52, v52
	v_exp_f32_e32 v53, v53
	v_exp_f32_e32 v40, v40
	v_add_f32_e32 v51, 1.0, v51
	v_add_f32_e32 v52, 1.0, v52
	v_add_f32_e32 v53, 1.0, v53
	v_add_f32_e32 v40, 1.0, v40
	v_rcp_f32_e32 v51, v51
	v_rcp_f32_e32 v52, v52
	v_rcp_f32_e32 v53, v53
	v_rcp_f32_e32 v55, v40
	v_pk_mul_f32 v[48:49], v[48:49], v[50:51]
	v_pk_mul_f32 v[46:47], v[46:47], v[52:53]
	v_pk_mul_f32 v[42:43], v[42:43], v[54:55]
.LBB0_539:
	v_add_u32_e32 v40, 0x90, v160
	v_ashrrev_i32_e32 v41, 31, v40
	v_mul_lo_u32 v50, s54, v41
	v_mul_lo_u32 v51, s55, v40
	v_mad_u64_u32 v[40:41], s[28:29], s54, v40, 0
	v_add3_u32 v41, v41, v50, v51
	s_mov_b32 s58, s56
	s_mov_b32 s59, s56
	v_lshl_add_u64 v[40:41], v[40:41], 1, v[120:121]
	v_pk_mul_f32 v[38:39], v[38:39], s[58:59]
	v_pk_mul_f32 v[36:37], v[36:37], s[56:57]
	v_pk_mul_f32 v[34:35], v[34:35], s[58:59]
	s_and_b64 vcc, exec, s[40:41]
	v_pk_mul_f32 v[32:33], v[32:33], s[56:57]
	v_cvt_pk_bf16_f32 v44, v44, v45
	v_cvt_pk_bf16_f32 v45, v46, v47
	v_cvt_pk_bf16_f32 v46, v48, v49
	v_cvt_pk_bf16_f32 v47, v42, v43
	s_nop 0
	s_bitcmp1_b32 s98, 0
	s_cbranch_scc0 .Lgi_keep10
	global_store_dwordx4 v[40:41], v[44:47], off sc1 nt
	s_branch .Lgi_done10
.Lgi_keep10:
	global_store_dwordx4 v[40:41], v[44:47], off sc1
.Lgi_done10:
	s_nop 1
	s_cbranch_vccnz .LBB0_541
	v_mul_f32_e32 v43, 0xbfb8aa3b, v32
	v_exp_f32_e32 v43, v43
	v_mul_f32_e32 v42, 0xbfb8aa3b, v36
	v_exp_f32_e32 v42, v42
	v_mul_f32_e32 v47, 0xbfb8aa3b, v34
	v_add_f32_e32 v43, 1.0, v43
	v_rcp_f32_e32 v44, v43
	v_mul_f32_e32 v43, 0xbfb8aa3b, v37
	v_exp_f32_e32 v43, v43
	v_add_f32_e32 v42, 1.0, v42
	v_exp_f32_e32 v47, v47
	v_rcp_f32_e32 v42, v42
	v_add_f32_e32 v43, 1.0, v43
	v_rcp_f32_e32 v43, v43
	v_add_f32_e32 v47, 1.0, v47
	v_mul_f32_e32 v45, 0xbfb8aa3b, v33
	v_mul_f32_e32 v46, 0xbfb8aa3b, v38
	v_rcp_f32_e32 v48, v47
	v_mul_f32_e32 v47, 0xbfb8aa3b, v39
	v_pk_mul_f32 v[36:37], v[36:37], v[42:43]
	v_mul_f32_e32 v42, 0xbfb8aa3b, v35
	v_exp_f32_e32 v45, v45
	v_exp_f32_e32 v46, v46
	v_exp_f32_e32 v47, v47
	v_exp_f32_e32 v42, v42
	v_add_f32_e32 v45, 1.0, v45
	v_add_f32_e32 v46, 1.0, v46
	v_add_f32_e32 v47, 1.0, v47
	v_add_f32_e32 v42, 1.0, v42
	v_rcp_f32_e32 v45, v45
	v_rcp_f32_e32 v46, v46
	v_rcp_f32_e32 v47, v47
	v_rcp_f32_e32 v49, v42
	v_pk_mul_f32 v[32:33], v[32:33], v[44:45]
	v_pk_mul_f32 v[38:39], v[38:39], v[46:47]
	v_pk_mul_f32 v[34:35], v[34:35], v[48:49]
.LBB0_541:
	v_cvt_pk_bf16_f32 v36, v36, v37
	v_cvt_pk_bf16_f32 v37, v38, v39
	v_cvt_pk_bf16_f32 v38, v32, v33
	v_pk_mul_f32 v[30:31], v[30:31], s[58:59]
	v_pk_mul_f32 v[28:29], v[28:29], s[56:57]
	v_pk_mul_f32 v[26:27], v[26:27], s[58:59]
	s_and_b64 vcc, exec, s[40:41]
	v_pk_mul_f32 v[32:33], v[24:25], s[56:57]
	v_lshl_add_u64 v[40:41], v[40:41], 0, s[4:5]
	v_cvt_pk_bf16_f32 v39, v34, v35
	s_nop 0
	s_bitcmp1_b32 s98, 0
	s_cbranch_scc0 .Lgi_keep11
	global_store_dwordx4 v[40:41], v[36:39], off sc1 nt
	s_branch .Lgi_done11
.Lgi_keep11:
	global_store_dwordx4 v[40:41], v[36:39], off sc1
.Lgi_done11:
	s_nop 1
	s_cbranch_vccnz .LBB0_543
	v_mul_f32_e32 v25, 0xbfb8aa3b, v32
	v_exp_f32_e32 v25, v25
	v_mul_f32_e32 v24, 0xbfb8aa3b, v28
	v_exp_f32_e32 v24, v24
	v_mul_f32_e32 v37, 0xbfb8aa3b, v26
	v_add_f32_e32 v25, 1.0, v25
	v_rcp_f32_e32 v34, v25
	v_mul_f32_e32 v25, 0xbfb8aa3b, v29
	v_exp_f32_e32 v25, v25
	v_add_f32_e32 v24, 1.0, v24
	v_exp_f32_e32 v37, v37
	v_rcp_f32_e32 v24, v24
	v_add_f32_e32 v25, 1.0, v25
	v_rcp_f32_e32 v25, v25
	v_add_f32_e32 v37, 1.0, v37
	v_mul_f32_e32 v35, 0xbfb8aa3b, v33
	v_mul_f32_e32 v36, 0xbfb8aa3b, v30
	v_rcp_f32_e32 v38, v37
	v_mul_f32_e32 v37, 0xbfb8aa3b, v31
	v_pk_mul_f32 v[28:29], v[28:29], v[24:25]
	v_mul_f32_e32 v24, 0xbfb8aa3b, v27
	v_exp_f32_e32 v35, v35
	v_exp_f32_e32 v36, v36
	v_exp_f32_e32 v37, v37
	v_exp_f32_e32 v24, v24
	v_add_f32_e32 v35, 1.0, v35
	v_add_f32_e32 v36, 1.0, v36
	v_add_f32_e32 v37, 1.0, v37
	v_add_f32_e32 v24, 1.0, v24
	v_rcp_f32_e32 v35, v35
	v_rcp_f32_e32 v36, v36
	v_rcp_f32_e32 v37, v37
	v_rcp_f32_e32 v39, v24
	v_pk_mul_f32 v[32:33], v[32:33], v[34:35]
	v_pk_mul_f32 v[30:31], v[30:31], v[36:37]
	v_pk_mul_f32 v[26:27], v[26:27], v[38:39]
.LBB0_543:
	v_add_u32_e32 v24, 0xa0, v160
	v_ashrrev_i32_e32 v25, 31, v24
	v_mul_lo_u32 v34, s54, v25
	v_mul_lo_u32 v35, s55, v24
	v_mad_u64_u32 v[24:25], s[28:29], s54, v24, 0
	v_add3_u32 v25, v25, v34, v35
	s_mov_b32 s58, s56
	s_mov_b32 s59, s56
	v_lshl_add_u64 v[24:25], v[24:25], 1, v[120:121]
	v_pk_mul_f32 v[22:23], v[22:23], s[58:59]
	v_pk_mul_f32 v[20:21], v[20:21], s[56:57]
	v_pk_mul_f32 v[18:19], v[18:19], s[58:59]
	s_and_b64 vcc, exec, s[40:41]
	v_pk_mul_f32 v[16:17], v[16:17], s[56:57]
	v_cvt_pk_bf16_f32 v28, v28, v29
	v_cvt_pk_bf16_f32 v29, v30, v31
	v_cvt_pk_bf16_f32 v30, v32, v33
	v_cvt_pk_bf16_f32 v31, v26, v27
	s_nop 0
	s_bitcmp1_b32 s98, 0
	s_cbranch_scc0 .Lgi_keep12
	global_store_dwordx4 v[24:25], v[28:31], off sc1 nt
	s_branch .Lgi_done12
.Lgi_keep12:
	global_store_dwordx4 v[24:25], v[28:31], off sc1
.Lgi_done12:
	s_nop 1
	s_cbranch_vccnz .LBB0_545
	v_mul_f32_e32 v27, 0xbfb8aa3b, v16
	v_exp_f32_e32 v27, v27
	v_mul_f32_e32 v26, 0xbfb8aa3b, v20
	v_exp_f32_e32 v26, v26
	v_mul_f32_e32 v31, 0xbfb8aa3b, v18
	v_add_f32_e32 v27, 1.0, v27
	v_rcp_f32_e32 v28, v27
	v_mul_f32_e32 v27, 0xbfb8aa3b, v21
	v_exp_f32_e32 v27, v27
	v_add_f32_e32 v26, 1.0, v26
	v_exp_f32_e32 v31, v31
	v_rcp_f32_e32 v26, v26
	v_add_f32_e32 v27, 1.0, v27
	v_rcp_f32_e32 v27, v27
	v_add_f32_e32 v31, 1.0, v31
	v_mul_f32_e32 v29, 0xbfb8aa3b, v17
	v_mul_f32_e32 v30, 0xbfb8aa3b, v22
	v_rcp_f32_e32 v32, v31
	v_mul_f32_e32 v31, 0xbfb8aa3b, v23
	v_pk_mul_f32 v[20:21], v[20:21], v[26:27]
	v_mul_f32_e32 v26, 0xbfb8aa3b, v19
	v_exp_f32_e32 v29, v29
	v_exp_f32_e32 v30, v30
	v_exp_f32_e32 v31, v31
	v_exp_f32_e32 v26, v26
	v_add_f32_e32 v29, 1.0, v29
	v_add_f32_e32 v30, 1.0, v30
	v_add_f32_e32 v31, 1.0, v31
	v_add_f32_e32 v26, 1.0, v26
	v_rcp_f32_e32 v29, v29
	v_rcp_f32_e32 v30, v30
	v_rcp_f32_e32 v31, v31
	v_rcp_f32_e32 v33, v26
	v_pk_mul_f32 v[16:17], v[16:17], v[28:29]
	v_pk_mul_f32 v[22:23], v[22:23], v[30:31]
	v_pk_mul_f32 v[18:19], v[18:19], v[32:33]
.LBB0_545:
	v_cvt_pk_bf16_f32 v20, v20, v21
	v_cvt_pk_bf16_f32 v21, v22, v23
	v_cvt_pk_bf16_f32 v22, v16, v17
	v_pk_mul_f32 v[14:15], v[14:15], s[58:59]
	v_pk_mul_f32 v[12:13], v[12:13], s[56:57]
	v_pk_mul_f32 v[10:11], v[10:11], s[58:59]
	s_and_b64 vcc, exec, s[40:41]
	v_pk_mul_f32 v[16:17], v[8:9], s[56:57]
	v_lshl_add_u64 v[24:25], v[24:25], 0, s[4:5]
	v_cvt_pk_bf16_f32 v23, v18, v19
	s_nop 0
	s_bitcmp1_b32 s98, 0
	s_cbranch_scc0 .Lgi_keep13
	global_store_dwordx4 v[24:25], v[20:23], off sc1 nt
	s_branch .Lgi_done13
.Lgi_keep13:
	global_store_dwordx4 v[24:25], v[20:23], off sc1
.Lgi_done13:
	s_nop 1
	s_cbranch_vccnz .LBB0_547
	v_mul_f32_e32 v9, 0xbfb8aa3b, v16
	v_exp_f32_e32 v9, v9
	v_mul_f32_e32 v8, 0xbfb8aa3b, v12
	v_exp_f32_e32 v8, v8
	v_mul_f32_e32 v21, 0xbfb8aa3b, v10
	v_add_f32_e32 v9, 1.0, v9
	v_rcp_f32_e32 v18, v9
	v_mul_f32_e32 v9, 0xbfb8aa3b, v13
	v_exp_f32_e32 v9, v9
	v_add_f32_e32 v8, 1.0, v8
	v_exp_f32_e32 v21, v21
	v_rcp_f32_e32 v8, v8
	v_add_f32_e32 v9, 1.0, v9
	v_rcp_f32_e32 v9, v9
	v_add_f32_e32 v21, 1.0, v21
	v_mul_f32_e32 v19, 0xbfb8aa3b, v17
	v_mul_f32_e32 v20, 0xbfb8aa3b, v14
	v_rcp_f32_e32 v22, v21
	v_mul_f32_e32 v21, 0xbfb8aa3b, v15
	v_pk_mul_f32 v[12:13], v[12:13], v[8:9]
	v_mul_f32_e32 v8, 0xbfb8aa3b, v11
	v_exp_f32_e32 v19, v19
	v_exp_f32_e32 v20, v20
	v_exp_f32_e32 v21, v21
	v_exp_f32_e32 v8, v8
	v_add_f32_e32 v19, 1.0, v19
	v_add_f32_e32 v20, 1.0, v20
	v_add_f32_e32 v21, 1.0, v21
	v_add_f32_e32 v8, 1.0, v8
	v_rcp_f32_e32 v19, v19
	v_rcp_f32_e32 v20, v20
	v_rcp_f32_e32 v21, v21
	v_rcp_f32_e32 v23, v8
	v_pk_mul_f32 v[16:17], v[16:17], v[18:19]
	v_pk_mul_f32 v[14:15], v[14:15], v[20:21]
	v_pk_mul_f32 v[10:11], v[10:11], v[22:23]
.LBB0_547:
	v_add_u32_e32 v8, 0xb0, v160
	v_ashrrev_i32_e32 v9, 31, v8
	v_mul_lo_u32 v18, s54, v9
	v_mul_lo_u32 v19, s55, v8
	v_mad_u64_u32 v[8:9], s[28:29], s54, v8, 0
	v_add3_u32 v9, v9, v18, v19
	s_mov_b32 s28, s56
	s_mov_b32 s29, s56
	v_lshl_add_u64 v[8:9], v[8:9], 1, v[120:121]
	v_pk_mul_f32 v[6:7], v[6:7], s[28:29]
	v_pk_mul_f32 v[4:5], v[4:5], s[56:57]
	v_pk_mul_f32 v[2:3], v[2:3], s[28:29]
	s_and_b64 vcc, exec, s[40:41]
	v_pk_mul_f32 v[0:1], v[0:1], s[56:57]
	v_cvt_pk_bf16_f32 v12, v12, v13
	v_cvt_pk_bf16_f32 v13, v14, v15
	v_cvt_pk_bf16_f32 v14, v16, v17
	v_cvt_pk_bf16_f32 v15, v10, v11
	s_nop 0
	s_bitcmp1_b32 s98, 0
	s_cbranch_scc0 .Lgi_keep14
	global_store_dwordx4 v[8:9], v[12:15], off sc1 nt
	s_branch .Lgi_done14
.Lgi_keep14:
	global_store_dwordx4 v[8:9], v[12:15], off sc1
.Lgi_done14:
	s_nop 1
	s_cbranch_vccnz .LBB0_549
	v_mul_f32_e32 v11, 0xbfb8aa3b, v0
	v_exp_f32_e32 v11, v11
	v_mul_f32_e32 v10, 0xbfb8aa3b, v4
	v_exp_f32_e32 v10, v10
	v_mul_f32_e32 v15, 0xbfb8aa3b, v2
	v_add_f32_e32 v11, 1.0, v11
	v_rcp_f32_e32 v12, v11
	v_mul_f32_e32 v11, 0xbfb8aa3b, v5
	v_exp_f32_e32 v11, v11
	v_add_f32_e32 v10, 1.0, v10
	v_exp_f32_e32 v15, v15
	v_rcp_f32_e32 v10, v10
	v_add_f32_e32 v11, 1.0, v11
	v_rcp_f32_e32 v11, v11
	v_add_f32_e32 v15, 1.0, v15
	v_mul_f32_e32 v13, 0xbfb8aa3b, v1
	v_mul_f32_e32 v14, 0xbfb8aa3b, v6
	v_rcp_f32_e32 v16, v15
	v_mul_f32_e32 v15, 0xbfb8aa3b, v7
	v_pk_mul_f32 v[4:5], v[4:5], v[10:11]
	v_mul_f32_e32 v10, 0xbfb8aa3b, v3
	v_exp_f32_e32 v13, v13
	v_exp_f32_e32 v14, v14
	v_exp_f32_e32 v15, v15
	v_exp_f32_e32 v10, v10
	v_add_f32_e32 v13, 1.0, v13
	v_add_f32_e32 v14, 1.0, v14
	v_add_f32_e32 v15, 1.0, v15
	v_add_f32_e32 v10, 1.0, v10
	v_rcp_f32_e32 v13, v13
	v_rcp_f32_e32 v14, v14
	v_rcp_f32_e32 v15, v15
	v_rcp_f32_e32 v17, v10
	v_pk_mul_f32 v[0:1], v[0:1], v[12:13]
	v_pk_mul_f32 v[6:7], v[6:7], v[14:15]
	v_pk_mul_f32 v[2:3], v[2:3], v[16:17]
.LBB0_549:
	s_andn2_b64 vcc, exec, s[38:39]
	s_mov_b64 s[38:39], -1
	v_lshl_add_u64 v[8:9], v[8:9], 0, s[4:5]
	v_cvt_pk_bf16_f32 v4, v4, v5
	v_cvt_pk_bf16_f32 v5, v6, v7
	v_cvt_pk_bf16_f32 v6, v0, v1
	v_cvt_pk_bf16_f32 v7, v2, v3
	s_nop 0
	s_bitcmp1_b32 s98, 0
	s_cbranch_scc0 .Lgi_keep15
	global_store_dwordx4 v[8:9], v[4:7], off sc1 nt
	s_branch .Lgi_done15
.Lgi_keep15:
	global_store_dwordx4 v[8:9], v[4:7], off sc1
.Lgi_done15:
	s_nop 1
	s_cbranch_vccnz .LBB0_498
	s_andn2_b64 vcc, exec, s[42:43]
	s_cbranch_vccnz .LBB0_497
	s_barrier
	s_branch .LBB0_497

.LBB0_637:
	s_or_b64 exec, exec, s[84:85]
	s_waitcnt lgkmcnt(0)
	v_add_f32_e32 v172, v172, v173
	v_add_f32_e32 v171, v172, v171
	v_add_f32_e32 v24, v24, v171
	ds_write_b32 v158, v24
	v_add_f32_e32 v24, v25, v171
	v_add_f32_e32 v25, v26, v171
	ds_write2_b32 v159, v24, v25 offset1:132
	v_add_f32_e32 v24, v27, v171
	v_add_f32_e32 v25, v62, v171
	v_add_u32_e32 v26, 0x400, v159
	ds_write2_b32 v26, v24, v25 offset0:8 offset1:140
	v_add_f32_e32 v24, v63, v171
	v_add_f32_e32 v25, v142, v171
	v_add_u32_e32 v26, 0x800, v159
	ds_write2_b32 v26, v24, v25 offset0:16 offset1:148
	v_add_f32_e32 v24, v187, v171
	v_add_f32_e32 v25, v188, v171
	v_add_u32_e32 v26, 0xc00, v159
	s_lshl_b32 s20, s36, 4
	s_lshl_b32 s28, s37, 2
	ds_write2_b32 v26, v24, v25 offset0:24 offset1:156
	v_add_f32_e32 v24, v189, v171
	v_add_f32_e32 v25, v190, v171
	v_add_u32_e32 v26, 0x1000, v159
	s_or_b32 s20, s28, s20
	ds_write2_b32 v26, v24, v25 offset0:32 offset1:164
	v_add_f32_e32 v24, v191, v171
	v_add_f32_e32 v25, v192, v171
	v_add_u32_e32 v26, 0x1400, v159
	s_add_i32 s84, s20, s95
	ds_write2_b32 v26, v24, v25 offset0:40 offset1:172
	v_add_f32_e32 v24, v193, v171
	v_add_f32_e32 v25, v194, v171
	v_add_u32_e32 v26, 0x1800, v159
	ds_write2_b32 v26, v24, v25 offset0:48 offset1:180
	v_add_f32_e32 v24, v170, v171
	s_ashr_i32 s85, s84, 31
	ds_write_b32 v159, v24 offset:7392
	v_add_u32_e32 v24, v71, v84
	s_lshl_b64 s[28:29], s[84:85], 15
	s_waitcnt lgkmcnt(0)
	s_barrier
	ds_read_b128 v[24:27], v24
	v_lshl_add_u64 v[62:63], v[60:61], 0, s[28:29]
	v_lshl_add_u64 v[170:171], v[38:39], 2, v[62:63]
	s_waitcnt lgkmcnt(0)
	global_store_dwordx4 v[170:171], v[24:27], off sc1 nt
	s_nop 1
	v_add_u32_e32 v24, v71, v85
	ds_read_b128 v[24:27], v24
	v_lshl_add_u64 v[170:171], v[40:41], 2, v[62:63]
	s_waitcnt lgkmcnt(0)
	global_store_dwordx4 v[170:171], v[24:27], off sc1 nt
	s_nop 1
	v_add_u32_e32 v24, v71, v86
	ds_read_b128 v[24:27], v24
	v_lshl_add_u64 v[170:171], v[42:43], 2, v[62:63]
	s_waitcnt lgkmcnt(0)
	global_store_dwordx4 v[170:171], v[24:27], off sc1 nt
	s_nop 1
	v_add_u32_e32 v24, v71, v87
	ds_read_b128 v[24:27], v24
	v_lshl_add_u64 v[62:63], v[44:45], 2, v[62:63]
	s_waitcnt lgkmcnt(0)
	global_store_dwordx4 v[62:63], v[24:27], off sc1 nt
	s_nop 1
	ds_read_b128 v[24:27], v72 offset:33264
	ds_read_b128 v[170:173], v72 offset:33280
	v_lshlrev_b32_e32 v62, 16, v0
	v_and_b32_e32 v63, 0xffff0000, v0
	v_lshlrev_b32_e32 v142, 16, v1
	v_and_b32_e32 v178, 0xffff0000, v1
	v_lshlrev_b32_e32 v179, 16, v2
	ds_read_b128 v[174:177], v160
	v_and_b32_e32 v180, 0xffff0000, v2
	v_lshlrev_b32_e32 v181, 16, v3
	v_and_b32_e32 v182, 0xffff0000, v3
	ds_read_b128 v[0:3], v160 offset:16
	s_waitcnt lgkmcnt(1)
	v_sub_f32_e32 v174, v24, v174
	v_sub_f32_e32 v175, v25, v175
	v_sub_f32_e32 v176, v26, v176
	v_sub_f32_e32 v177, v27, v177
	s_waitcnt lgkmcnt(0)
	v_sub_f32_e32 v3, v173, v3
	v_sub_f32_e32 v0, v170, v0
	v_sub_f32_e32 v1, v171, v1
	v_sub_f32_e32 v2, v172, v2
	v_mul_f32_e32 v3, 0x3fb8aa3b, v3
	v_mul_f32_e32 v174, 0x3fb8aa3b, v174
	v_mul_f32_e32 v175, 0x3fb8aa3b, v175
	v_mul_f32_e32 v176, 0x3fb8aa3b, v176
	v_mul_f32_e32 v177, 0x3fb8aa3b, v177
	v_mul_f32_e32 v0, 0x3fb8aa3b, v0
	v_mul_f32_e32 v1, 0x3fb8aa3b, v1
	v_mul_f32_e32 v2, 0x3fb8aa3b, v2
	v_exp_f32_e32 v3, v3
	v_exp_f32_e32 v174, v174
	v_exp_f32_e32 v175, v175
	v_exp_f32_e32 v176, v176
	v_exp_f32_e32 v177, v177
	v_exp_f32_e32 v0, v0
	v_exp_f32_e32 v1, v1
	v_exp_f32_e32 v2, v2
	v_mul_f32_e32 v3, v3, v182
	v_mul_f32_e32 v62, v174, v62
	v_mul_f32_e32 v63, v175, v63
	v_mul_f32_e32 v142, v176, v142
	v_mul_f32_e32 v174, v177, v178
	v_mul_f32_e32 v175, v0, v179
	v_mul_f32_e32 v176, v1, v180
	v_mul_f32_e32 v177, v2, v181
	v_cvt_pk_bf16_f32 v0, v62, v63
	v_cvt_pk_bf16_f32 v1, v142, v174
	v_cvt_pk_bf16_f32 v2, v175, v176
	v_cvt_pk_bf16_f32 v3, v177, v3
	ds_write_b128 v169, v[0:3] offset:41984
	ds_read_b128 v[0:3], v160 offset:16896
	v_lshlrev_b32_e32 v62, 16, v16
	v_and_b32_e32 v63, 0xffff0000, v16
	v_lshlrev_b32_e32 v142, 16, v17
	v_and_b32_e32 v174, 0xffff0000, v17
	v_lshlrev_b32_e32 v175, 16, v18
	v_and_b32_e32 v176, 0xffff0000, v18
	v_lshlrev_b32_e32 v177, 16, v19
	v_and_b32_e32 v178, 0xffff0000, v19
	ds_read_b128 v[16:19], v160 offset:16912
	s_waitcnt lgkmcnt(1)
	v_sub_f32_e32 v0, v24, v0
	v_sub_f32_e32 v1, v25, v1
	v_sub_f32_e32 v2, v26, v2
	v_sub_f32_e32 v3, v27, v3
	v_mul_f32_e32 v0, 0x3fb8aa3b, v0
	v_mul_f32_e32 v1, 0x3fb8aa3b, v1
	v_mul_f32_e32 v2, 0x3fb8aa3b, v2
	v_mul_f32_e32 v3, 0x3fb8aa3b, v3
	s_waitcnt lgkmcnt(0)
	v_sub_f32_e32 v16, v170, v16
	v_sub_f32_e32 v17, v171, v17
	v_sub_f32_e32 v18, v172, v18
	v_sub_f32_e32 v19, v173, v19
	v_exp_f32_e32 v0, v0
	v_exp_f32_e32 v1, v1
	v_exp_f32_e32 v2, v2
	v_exp_f32_e32 v3, v3
	v_mul_f32_e32 v16, 0x3fb8aa3b, v16
	v_mul_f32_e32 v17, 0x3fb8aa3b, v17
	v_mul_f32_e32 v18, 0x3fb8aa3b, v18
	v_mul_f32_e32 v19, 0x3fb8aa3b, v19
	v_exp_f32_e32 v16, v16
	v_exp_f32_e32 v17, v17
	v_exp_f32_e32 v18, v18
	v_exp_f32_e32 v19, v19
	v_mul_f32_e32 v0, v0, v62
	v_mul_f32_e32 v1, v1, v63
	v_mul_f32_e32 v2, v2, v142
	v_mul_f32_e32 v3, v3, v174
	v_mul_f32_e32 v16, v16, v175
	v_mul_f32_e32 v17, v17, v176
	v_mul_f32_e32 v18, v18, v177
	v_mul_f32_e32 v19, v19, v178
	v_cvt_pk_bf16_f32 v0, v0, v1
	v_cvt_pk_bf16_f32 v1, v2, v3
	v_cvt_pk_bf16_f32 v2, v16, v17
	v_cvt_pk_bf16_f32 v3, v18, v19
	ds_write_b128 v169, v[0:3] offset:50688
	s_and_saveexec_b64 s[86:87], s[80:81]
	s_cbranch_execz .LBB0_608
	ds_read_b32 v0, v69 offset:33264
	s_lshl_b64 s[28:29], s[84:85], 9
	s_waitcnt lgkmcnt(0)
	v_mul_f32_e32 v0, 0x3fb8aa3b, v0
	v_exp_f32_e32 v2, v0
	v_lshl_add_u64 v[0:1], v[34:35], 0, s[28:29]
	global_store_dword v[0:1], v2, off sc1
	s_branch .LBB0_608
